# spin-poll back-off removal: s_sleep 1 -> s_sleep 0 in the four poll loops (on v32)
# baseline (speedup 1.0000x reference)
; __device__ __forceinline__ unsigned xb_ld(unsigned* p)              { return __hip_atomic_load(p, __ATOMIC_RELAXED, __HIP_MEMORY_SCOPE_AGENT); }
; __device__ __forceinline__ void xcd_barrier_complete(unsigned* bar, unsigned x, unsigned& nloc, unsigned& nx) {
;     const unsigned G = gridDim.x * gridDim.y * gridDim.z;
;     unsigned sum, cnt, mine, sp = 0u;
;     for (;;) {
;         sum = 0u; cnt = 0u; mine = 0u;
; #pragma unroll
;         for (unsigned j = 0; j < 16; ++j) { const unsigned c = xb_ld(&bar[XB_XCNT(j)]); sum += c; cnt += (c > 0u) ? 1u : 0u; mine = (j == x) ? c : mine; }
;         if (sum == G) break;
;         __builtin_amdgcn_s_sleep(1);
;         if ((++sp & 255u) == 0u) { if (xb_ld(&bar[XB_TMO])) break; if (sp > XB_SPIN_CAP) { atomicAdd(&bar[XB_TMO], 1u); break; } }
;     }
.LBB0_37:
	global_load_dword v16, v1, s[80:81] sc1
	global_load_dword v0, v1, s[60:61] sc1
	s_waitcnt lgkmcnt(0)
	global_load_dword v2, v1, s[62:63] sc1
	global_load_dword v3, v1, s[66:67] sc1
	global_load_dword v4, v1, s[54:55] sc1
	global_load_dword v5, v1, s[56:57] sc1
	global_load_dword v6, v1, s[58:59] sc1
	global_load_dword v7, v1, s[74:75] sc1
	global_load_dword v8, v1, s[12:13] sc1
	global_load_dword v9, v1, s[14:15] sc1
	global_load_dword v10, v1, s[16:17] sc1
	global_load_dword v11, v1, s[18:19] sc1
	global_load_dword v12, v1, s[20:21] sc1
	global_load_dword v13, v1, s[22:23] sc1
	global_load_dword v14, v1, s[24:25] sc1
	global_load_dword v15, v1, s[26:27] sc1
	s_mov_b64 s[4:5], -1
	s_mov_b64 s[6:7], -1
	s_waitcnt vmcnt(14)
	v_add_u32_e32 v17, v0, v16
	s_waitcnt vmcnt(13)
	v_add_u32_e32 v17, v17, v2
	s_waitcnt vmcnt(12)
	v_add_u32_e32 v17, v17, v3
	s_waitcnt vmcnt(11)
	v_add_u32_e32 v17, v17, v4
	s_waitcnt vmcnt(10)
	v_add_u32_e32 v17, v17, v5
	s_waitcnt vmcnt(9)
	v_add_u32_e32 v17, v17, v6
	s_waitcnt vmcnt(8)
	v_add_u32_e32 v17, v17, v7
	s_waitcnt vmcnt(7)
	v_add_u32_e32 v17, v17, v8
	s_waitcnt vmcnt(6)
	v_add_u32_e32 v17, v17, v9
	s_waitcnt vmcnt(5)
	v_add_u32_e32 v17, v17, v10
	s_waitcnt vmcnt(4)
	v_add_u32_e32 v17, v17, v11
	s_waitcnt vmcnt(3)
	v_add_u32_e32 v17, v17, v12
	s_waitcnt vmcnt(2)
	v_add_u32_e32 v17, v17, v13
	s_waitcnt vmcnt(1)
	v_add_u32_e32 v17, v17, v14
	s_waitcnt vmcnt(0)
	v_add_u32_e32 v17, v17, v15
	v_cmp_eq_u32_e32 vcc, s68, v17
	s_cbranch_vccnz .LBB0_36
	s_and_b32 s4, s10, 0xff
	s_cmp_eq_u32 s4, 0
	s_mov_b64 s[4:5], -1
	s_mov_b64 s[8:9], -1
	s_sleep 0
	s_cbranch_scc1 .LBB0_41
	s_and_b64 vcc, exec, s[8:9]
	s_cbranch_vccz .LBB0_36

; __device__ __forceinline__ unsigned xb_ld(unsigned* p)              { return __hip_atomic_load(p, __ATOMIC_RELAXED, __HIP_MEMORY_SCOPE_AGENT); }
; #define XB_SPIN(cond, bar) do { unsigned _sp = 0; while (cond) { __builtin_amdgcn_s_sleep(1); \
;     if ((++_sp & 255u) == 0u) { if (xb_ld(&(bar)[XB_TMO])) break; if (_sp > XB_SPIN_CAP) { atomicAdd(&(bar)[XB_TMO], 1u); break; } } } } while (0)
; __device__ __forceinline__ void xcd_barrier(const XcdBarrier& b) {
;     ...
;             else XB_SPIN(xb_ld(&bar[XB_TOPGEN]) == tg, bar);
;     ...
;             XB_SPIN(xb_ld(&bar[XB_XGEN(b.x)]) == gen, bar);
.LBB0_68:
	s_and_b32 s14, s18, 0xff
	s_mov_b64 s[12:13], -1
	s_cmp_lg_u32 s14, 0
	s_mov_b64 s[16:17], -1
	s_sleep 0
	s_cbranch_scc0 .LBB0_71
	s_and_b64 vcc, exec, s[16:17]
	s_cbranch_vccz .LBB0_67

; __global__ void __launch_bounds__(512, 2) mk_fwd(Args a) {
;     ...
;         if (sync_after && ph + 1 < a.ph_hi) { if (ph == a.ph_lo) grid.sync(); else xcd_barrier(xbar); }
.LBB0_507:
	s_sleep 0
	global_load_dword v2, v1, s[4:5] offset:32 sc1
	s_waitcnt vmcnt(0)
	v_and_b32_e32 v2, 0xffff0000, v2
	v_cmp_ne_u32_e32 vcc, v2, v0
	s_or_b64 s[6:7], vcc, s[6:7]
	s_andn2_b64 exec, exec, s[6:7]
	s_cbranch_execnz .LBB0_507
	s_branch .LBB0_9
